# AP3 + G_in/G_up accumulator pairs ordered so that consecutive MFMAs at pair boundaries share an A or B operand (k order flipped in alternate pairs; same products, different association order)
# speedup vs baseline: 1.0025x; 1.0025x over previous
; #define PG8_SB(B) __builtin_amdgcn_rcpf(1.f + expneg(B))
; #define PG8_SB(B) __builtin_amdgcn_rcpf(1.f + expneg(B))
; #define PG8_STAGE(bufoff, gbase, voff) do { _Pragma("unroll") for (int _i = 0; _i < 2; ++_i) \
;         __builtin_amdgcn_global_load_lds((const unsigned*)((const char*)(gbase) + (size_t)_i * qstep + (voff)[0]), (PG8_LAS unsigned*)(lds + (bufoff) + ldsw + _i * 8192), 16, 0, 0); } while (0)
; #define PG8_LDA(dst, b, h) do { _Pragma("unroll") for (int m = 0; m < 4; ++m) _Pragma("unroll") for (int k = 0; k < 2; ++k) dst[m][k] = *(const PG8_LAS bf16x8*)(lds + PG8_SA(b, h) + aoff + m * 2048 + k * 1024); } while (0)
; #define PG8_MMA(ai, bj, At, Bt) do { __builtin_amdgcn_s_setprio(1); _Pragma("unroll") for (int m = 0; m < 4; ++m) _Pragma("unroll") for (int n = 0; n < 2; ++n) _Pragma("unroll") for (int k = 0; k < 2; ++k) \
;         acc[ai][bj][m][n] = __builtin_amdgcn_mfma_f32_16x16x32_bf16(Bt[n][k], At[m][k], acc[ai][bj][m][n], 0, 0, 0); __builtin_amdgcn_s_setprio(0); } while (0)
; #define PG8_WAIT_V89() do { if constexpr (SLIVER) PG8_WAIT_V(9); else PG8_WAIT_V(8); } while (0)
; #define PG8_LDS_S(b) do { if constexpr (SLIVER) { Sf[0] = *(const PG8_LAS bf16x8*)(lds + STAGE_BYTES + (b) * 2048 + soff0); Sf[1] = *(const PG8_LAS bf16x8*)(lds + STAGE_BYTES + (b) * 2048 + (soff0 ^ 64)); } } while (0)
; #define PG8_WAIT_L(n) asm volatile("s_waitcnt lgkmcnt(" #n ")" ::: "memory")
; #define PG8_BAR __builtin_amdgcn_s_barrier()
; #define PG8_SCHED __builtin_amdgcn_sched_barrier(0)
; template <class Epi, class Sched, bool ALIGN_EPI = false, bool SP2 = false, bool SLIVER = false>
; __device__ __forceinline__ void gemm_phase(PG8_LAS unsigned char* lds, const Gemm g, const Sched& S, const Epi& E) {
;     ...
;             PG8_WAIT_V89(); PG8_WAIT_L(0); PG8_BAR; PG8_MMA(0, 0, At, B0); PG8_MMA(0, 1, At, B1); PG8_BAR; PG8_SCHED;
;             PG8_LDA(At, 0, 1); PG8_LDS_S(0); PG8_STAGE(PG8_SB(0, 0), b2, voffB); PG8_STAGE(PG8_SB(0, 1), b2 + hstep, voffB); PG8_STAGE(PG8_SA(0, 0), a2, voffA);
;             PG8_WAIT_V89(); PG8_WAIT_L(0); PG8_BAR; PG8_MMA(1, 0, At, B0); PG8_MMA(1, 1, At, B1); PG8_MMA_S(); PG8_BAR; PG8_SCHED;
.Lgin_skipw0:
	s_waitcnt lgkmcnt(0)
	s_setprio 1
	s_barrier
	v_mfma_f32_16x16x32_bf16 v[126:129], v[136:139], v[174:177], v[126:129]
	v_mfma_f32_16x16x32_bf16 v[126:129], v[140:143], v[180:183], v[126:129]
	v_mfma_f32_16x16x32_bf16 v[122:125], v[154:157], v[180:183], v[122:125]
	v_mfma_f32_16x16x32_bf16 v[122:125], v[150:153], v[174:177], v[122:125]
	v_mfma_f32_16x16x32_bf16 v[106:109], v[150:153], v[184:187], v[106:109]
	v_mfma_f32_16x16x32_bf16 v[106:109], v[154:157], v[188:191], v[106:109]
	v_mfma_f32_16x16x32_bf16 v[114:117], v[140:143], v[188:191], v[114:117]
	v_mfma_f32_16x16x32_bf16 v[114:117], v[136:139], v[184:187], v[114:117]
	v_mfma_f32_16x16x32_bf16 v[98:101], v[136:139], v[192:195], v[98:101]
	v_mfma_f32_16x16x32_bf16 v[98:101], v[140:143], v[196:199], v[98:101]
	v_mfma_f32_16x16x32_bf16 v[90:93], v[154:157], v[196:199], v[90:93]
	v_mfma_f32_16x16x32_bf16 v[90:93], v[150:153], v[192:195], v[90:93]
	v_mfma_f32_16x16x32_bf16 v[74:77], v[150:153], v[200:203], v[74:77]
	v_mfma_f32_16x16x32_bf16 v[74:77], v[154:157], v[210:213], v[74:77]
	v_mfma_f32_16x16x32_bf16 v[82:85], v[140:143], v[210:213], v[82:85]
	v_mfma_f32_16x16x32_bf16 v[82:85], v[136:139], v[200:203], v[82:85]
	s_setprio 0
	s_setprio 1
	v_mfma_f32_16x16x32_bf16 v[118:121], v[158:161], v[174:177], v[118:121]
	v_mfma_f32_16x16x32_bf16 v[118:121], v[162:165], v[180:183], v[118:121]
	v_mfma_f32_16x16x32_bf16 v[110:113], v[170:173], v[180:183], v[110:113]
	v_mfma_f32_16x16x32_bf16 v[110:113], v[166:169], v[174:177], v[110:113]
	v_mfma_f32_16x16x32_bf16 v[94:97], v[166:169], v[184:187], v[94:97]
	v_mfma_f32_16x16x32_bf16 v[94:97], v[170:173], v[188:191], v[94:97]
	v_mfma_f32_16x16x32_bf16 v[102:105], v[162:165], v[188:191], v[102:105]
	v_mfma_f32_16x16x32_bf16 v[102:105], v[158:161], v[184:187], v[102:105]
	v_mfma_f32_16x16x32_bf16 v[86:89], v[158:161], v[192:195], v[86:89]
	v_mfma_f32_16x16x32_bf16 v[86:89], v[162:165], v[196:199], v[86:89]
	v_mfma_f32_16x16x32_bf16 v[78:81], v[170:173], v[196:199], v[78:81]
	v_mfma_f32_16x16x32_bf16 v[78:81], v[166:169], v[192:195], v[78:81]
	v_mfma_f32_16x16x32_bf16 v[66:69], v[166:169], v[200:203], v[66:69]
	v_mfma_f32_16x16x32_bf16 v[66:69], v[170:173], v[210:213], v[66:69]
	v_mfma_f32_16x16x32_bf16 v[70:73], v[162:165], v[210:213], v[70:73]
	v_mfma_f32_16x16x32_bf16 v[70:73], v[158:161], v[200:203], v[70:73]
	s_barrier
	s_setprio 0
	s_add_i32 s77, s77, s53
	s_mov_b32 m0, s77
	ds_read_b128 v[174:177], v149 offset:16384
	ds_read_b128 v[180:183], v149 offset:17408
	ds_read_b128 v[184:187], v149 offset:18432
	ds_read_b128 v[188:191], v149 offset:19456
	ds_read_b128 v[192:195], v149 offset:20480
	ds_read_b128 v[196:199], v149 offset:21504
	ds_read_b128 v[200:203], v149 offset:22528
	ds_read_b128 v[210:213], v149 offset:23552
	global_load_lds_dwordx4 v132, s[78:79]
	s_add_i32 m0, s77, 0x2000
	s_add_i32 s77, s80, s53
	s_add_u32 s58, s78, 0x40000
	s_addc_u32 s59, s79, 0
	global_load_lds_dwordx4 v132, s[58:59]
	s_mov_b32 m0, s77
	s_nop 0
	s_add_u32 s60, s78, 0x80000
	s_addc_u32 s61, s79, 0
	global_load_lds_dwordx4 v132, s[60:61]
	s_add_i32 m0, s77, 0x2000
	s_nop 0
	s_add_u32 s36, s78, 0xc0000
	s_addc_u32 s37, s79, 0
	global_load_lds_dwordx4 v132, s[36:37]
	s_mov_b64 s[46:47], s[62:63]
	s_mov_b32 m0, s91
	s_nop 0
	global_load_lds_dwordx4 v130, s[46:47]
	s_mov_b32 m0, s50
	s_nop 0
	s_add_u32 s58, s46, 0x40000
	s_addc_u32 s59, s47, 0
	global_load_lds_dwordx4 v130, s[58:59]
	s_cmp_eq_u32 s76, s101
	s_cbranch_scc1 .Lgin_skipw1
	s_waitcnt vmcnt(8)
.Lgin_skipw1:
	s_waitcnt lgkmcnt(0)
	s_setprio 1
	s_barrier
	v_mfma_f32_16x16x32_bf16 v[62:65], v[136:139], v[174:177], v[62:65]
	v_mfma_f32_16x16x32_bf16 v[62:65], v[140:143], v[180:183], v[62:65]
	v_mfma_f32_16x16x32_bf16 v[58:61], v[154:157], v[180:183], v[58:61]
	v_mfma_f32_16x16x32_bf16 v[58:61], v[150:153], v[174:177], v[58:61]
	v_mfma_f32_16x16x32_bf16 v[42:45], v[150:153], v[184:187], v[42:45]
	v_mfma_f32_16x16x32_bf16 v[42:45], v[154:157], v[188:191], v[42:45]
	v_mfma_f32_16x16x32_bf16 v[50:53], v[140:143], v[188:191], v[50:53]
	v_mfma_f32_16x16x32_bf16 v[50:53], v[136:139], v[184:187], v[50:53]
	v_mfma_f32_16x16x32_bf16 v[34:37], v[136:139], v[192:195], v[34:37]
	v_mfma_f32_16x16x32_bf16 v[34:37], v[140:143], v[196:199], v[34:37]
	v_mfma_f32_16x16x32_bf16 v[26:29], v[154:157], v[196:199], v[26:29]
	v_mfma_f32_16x16x32_bf16 v[26:29], v[150:153], v[192:195], v[26:29]
	v_mfma_f32_16x16x32_bf16 v[10:13], v[150:153], v[200:203], v[10:13]
	v_mfma_f32_16x16x32_bf16 v[10:13], v[154:157], v[210:213], v[10:13]
	v_mfma_f32_16x16x32_bf16 v[18:21], v[140:143], v[210:213], v[18:21]
	v_mfma_f32_16x16x32_bf16 v[18:21], v[136:139], v[200:203], v[18:21]
	s_setprio 0
	s_setprio 1
	v_mfma_f32_16x16x32_bf16 v[54:57], v[158:161], v[174:177], v[54:57]
	v_mfma_f32_16x16x32_bf16 v[54:57], v[162:165], v[180:183], v[54:57]
	v_mfma_f32_16x16x32_bf16 v[46:49], v[170:173], v[180:183], v[46:49]
	v_mfma_f32_16x16x32_bf16 v[46:49], v[166:169], v[174:177], v[46:49]
	v_mfma_f32_16x16x32_bf16 v[30:33], v[166:169], v[184:187], v[30:33]
	v_mfma_f32_16x16x32_bf16 v[30:33], v[170:173], v[188:191], v[30:33]
	v_mfma_f32_16x16x32_bf16 v[38:41], v[162:165], v[188:191], v[38:41]
	v_mfma_f32_16x16x32_bf16 v[38:41], v[158:161], v[184:187], v[38:41]
	v_mfma_f32_16x16x32_bf16 v[22:25], v[158:161], v[192:195], v[22:25]
	v_mfma_f32_16x16x32_bf16 v[22:25], v[162:165], v[196:199], v[22:25]
	v_mfma_f32_16x16x32_bf16 v[14:17], v[170:173], v[196:199], v[14:17]
	v_mfma_f32_16x16x32_bf16 v[14:17], v[166:169], v[192:195], v[14:17]
	v_mfma_f32_16x16x32_bf16 v[2:5], v[166:169], v[200:203], v[2:5]
	v_mfma_f32_16x16x32_bf16 v[2:5], v[170:173], v[210:213], v[2:5]
	v_mfma_f32_16x16x32_bf16 v[6:9], v[162:165], v[210:213], v[6:9]
	v_mfma_f32_16x16x32_bf16 v[6:9], v[158:161], v[200:203], v[6:9]
	s_barrier
; #define PG8_STAGE(bufoff, gbase, voff) do { _Pragma("unroll") for (int _i = 0; _i < 2; ++_i) \
;         __builtin_amdgcn_global_load_lds((const unsigned*)((const char*)(gbase) + (size_t)_i * qstep + (voff)[0]), (PG8_LAS unsigned*)(lds + (bufoff) + ldsw + _i * 8192), 16, 0, 0); } while (0)
; #define PG8_LDA(dst, b, h) do { _Pragma("unroll") for (int m = 0; m < 4; ++m) _Pragma("unroll") for (int k = 0; k < 2; ++k) dst[m][k] = *(const PG8_LAS bf16x8*)(lds + PG8_SA(b, h) + aoff + m * 2048 + k * 1024); } while (0)
; #define PG8_LDB(dst, b, h) do { _Pragma("unroll") for (int n = 0; n < 2; ++n) _Pragma("unroll") for (int k = 0; k < 2; ++k) dst[n][k] = *(const PG8_LAS bf16x8*)(lds + PG8_SB(b, h) + boff + n * 2048 + k * 1024); } while (0)
; #define PG8_MMA(ai, bj, At, Bt) do { __builtin_amdgcn_s_setprio(1); _Pragma("unroll") for (int m = 0; m < 4; ++m) _Pragma("unroll") for (int n = 0; n < 2; ++n) _Pragma("unroll") for (int k = 0; k < 2; ++k) \
;         acc[ai][bj][m][n] = __builtin_amdgcn_mfma_f32_16x16x32_bf16(Bt[n][k], At[m][k], acc[ai][bj][m][n], 0, 0, 0); __builtin_amdgcn_s_setprio(0); } while (0)
; #define PG8_WAIT_V89() do { if constexpr (SLIVER) PG8_WAIT_V(9); else PG8_WAIT_V(8); } while (0)
; #define PG8_STAGE_S(b, gbase) do { if constexpr (SLIVER) __builtin_amdgcn_global_load_lds((const unsigned*)((const char*)(gbase) + voffS), (PG8_LAS unsigned*)(lds + STAGE_BYTES + (b) * 2048 + wid * 256), 4, 0, 0); } while (0)
; #define PG8_WAIT_L(n) asm volatile("s_waitcnt lgkmcnt(" #n ")" ::: "memory")
; #define PG8_BAR __builtin_amdgcn_s_barrier()
; #define PG8_SCHED __builtin_amdgcn_sched_barrier(0)
; template <class Epi, class Sched, bool ALIGN_EPI = false, bool SP2 = false, bool SLIVER = false>
; __device__ __forceinline__ void gemm_phase(PG8_LAS unsigned char* lds, const Gemm g, const Sched& S, const Epi& E) {
;     ...
;             PG8_LDB(B0, 1, 0); PG8_LDB(B1, 1, 1); PG8_SCHED; PG8_LDA(At, 1, 0); PG8_STAGE(PG8_SA(0, 1), a2 + hstep, voffA); PG8_STAGE_S(0, s2);
;             PG8_WAIT_V89(); PG8_WAIT_L(0); PG8_BAR; PG8_MMA(0, 0, At, B0); PG8_MMA(0, 1, At, B1); PG8_BAR; PG8_SCHED;
	s_setprio 0
	s_add_i32 s62, 0, 0x18000
	v_add_u32_e32 v144, s62, v145
	s_add_i32 s63, 0, 0x1c000
	ds_read_b128 v[136:139], v144
	ds_read_b128 v[140:143], v144 offset:1024
	ds_read_b128 v[150:153], v144 offset:2048
	ds_read_b128 v[154:157], v144 offset:3072
	v_add_u32_e32 v144, s63, v145
	ds_read_b128 v[158:161], v144
	ds_read_b128 v[162:165], v144 offset:1024
	ds_read_b128 v[166:169], v144 offset:2048
	ds_read_b128 v[170:173], v144 offset:3072
	s_mov_b32 m0, s51
	ds_read_b128 v[174:177], v149 offset:32768
	ds_read_b128 v[180:183], v149 offset:33792
	ds_read_b128 v[184:187], v149 offset:34816
	ds_read_b128 v[188:191], v149 offset:35840
	ds_read_b128 v[192:195], v149 offset:36864
	ds_read_b128 v[196:199], v149 offset:37888
	ds_read_b128 v[200:203], v149 offset:38912
	ds_read_b128 v[210:213], v149 offset:39936
	s_add_u32 s60, s46, 0x80000
	s_addc_u32 s61, s47, 0
	global_load_lds_dwordx4 v130, s[60:61]
	s_mov_b32 m0, s54
	s_nop 0
	s_add_u32 s36, s46, 0xc0000
	s_addc_u32 s37, s47, 0
	global_load_lds_dwordx4 v130, s[36:37]
	s_waitcnt vmcnt(8)
	s_waitcnt lgkmcnt(0)
	s_setprio 1
	s_barrier
	v_mfma_f32_16x16x32_bf16 v[126:129], v[136:139], v[174:177], v[126:129]
	v_mfma_f32_16x16x32_bf16 v[126:129], v[140:143], v[180:183], v[126:129]
	v_mfma_f32_16x16x32_bf16 v[122:125], v[154:157], v[180:183], v[122:125]
	v_mfma_f32_16x16x32_bf16 v[122:125], v[150:153], v[174:177], v[122:125]
	v_mfma_f32_16x16x32_bf16 v[106:109], v[150:153], v[184:187], v[106:109]
	v_mfma_f32_16x16x32_bf16 v[106:109], v[154:157], v[188:191], v[106:109]
	v_mfma_f32_16x16x32_bf16 v[114:117], v[140:143], v[188:191], v[114:117]
	v_mfma_f32_16x16x32_bf16 v[114:117], v[136:139], v[184:187], v[114:117]
	v_mfma_f32_16x16x32_bf16 v[98:101], v[136:139], v[192:195], v[98:101]
	v_mfma_f32_16x16x32_bf16 v[98:101], v[140:143], v[196:199], v[98:101]
	v_mfma_f32_16x16x32_bf16 v[90:93], v[154:157], v[196:199], v[90:93]
	v_mfma_f32_16x16x32_bf16 v[90:93], v[150:153], v[192:195], v[90:93]
	v_mfma_f32_16x16x32_bf16 v[74:77], v[150:153], v[200:203], v[74:77]
	v_mfma_f32_16x16x32_bf16 v[74:77], v[154:157], v[210:213], v[74:77]
	v_mfma_f32_16x16x32_bf16 v[82:85], v[140:143], v[210:213], v[82:85]
	v_mfma_f32_16x16x32_bf16 v[82:85], v[136:139], v[200:203], v[82:85]
	s_setprio 0
	s_setprio 1
	v_mfma_f32_16x16x32_bf16 v[118:121], v[158:161], v[174:177], v[118:121]
	v_mfma_f32_16x16x32_bf16 v[118:121], v[162:165], v[180:183], v[118:121]
	v_mfma_f32_16x16x32_bf16 v[110:113], v[170:173], v[180:183], v[110:113]
	v_mfma_f32_16x16x32_bf16 v[110:113], v[166:169], v[174:177], v[110:113]
	v_mfma_f32_16x16x32_bf16 v[94:97], v[166:169], v[184:187], v[94:97]
	v_mfma_f32_16x16x32_bf16 v[94:97], v[170:173], v[188:191], v[94:97]
	v_mfma_f32_16x16x32_bf16 v[102:105], v[162:165], v[188:191], v[102:105]
	v_mfma_f32_16x16x32_bf16 v[102:105], v[158:161], v[184:187], v[102:105]
	v_mfma_f32_16x16x32_bf16 v[86:89], v[158:161], v[192:195], v[86:89]
	v_mfma_f32_16x16x32_bf16 v[86:89], v[162:165], v[196:199], v[86:89]
	v_mfma_f32_16x16x32_bf16 v[78:81], v[170:173], v[196:199], v[78:81]
	v_mfma_f32_16x16x32_bf16 v[78:81], v[166:169], v[192:195], v[78:81]
	v_mfma_f32_16x16x32_bf16 v[66:69], v[166:169], v[200:203], v[66:69]
	v_mfma_f32_16x16x32_bf16 v[66:69], v[170:173], v[210:213], v[66:69]
	v_mfma_f32_16x16x32_bf16 v[70:73], v[162:165], v[210:213], v[70:73]
	v_mfma_f32_16x16x32_bf16 v[70:73], v[158:161], v[200:203], v[70:73]
	s_barrier
; #define PG8_SB(B) __builtin_amdgcn_rcpf(1.f + expneg(B))
; #define PG8_SB(B) __builtin_amdgcn_rcpf(1.f + expneg(B))
; #define PG8_STAGE(bufoff, gbase, voff) do { _Pragma("unroll") for (int _i = 0; _i < 2; ++_i) \
;         __builtin_amdgcn_global_load_lds((const unsigned*)((const char*)(gbase) + (size_t)_i * qstep + (voff)[0]), (PG8_LAS unsigned*)(lds + (bufoff) + ldsw + _i * 8192), 16, 0, 0); } while (0)
; #define PG8_LDA(dst, b, h) do { _Pragma("unroll") for (int m = 0; m < 4; ++m) _Pragma("unroll") for (int k = 0; k < 2; ++k) dst[m][k] = *(const PG8_LAS bf16x8*)(lds + PG8_SA(b, h) + aoff + m * 2048 + k * 1024); } while (0)
; #define PG8_MMA(ai, bj, At, Bt) do { __builtin_amdgcn_s_setprio(1); _Pragma("unroll") for (int m = 0; m < 4; ++m) _Pragma("unroll") for (int n = 0; n < 2; ++n) _Pragma("unroll") for (int k = 0; k < 2; ++k) \
;         acc[ai][bj][m][n] = __builtin_amdgcn_mfma_f32_16x16x32_bf16(Bt[n][k], At[m][k], acc[ai][bj][m][n], 0, 0, 0); __builtin_amdgcn_s_setprio(0); } while (0)
; #define PG8_WAIT_V89() do { if constexpr (SLIVER) PG8_WAIT_V(9); else PG8_WAIT_V(8); } while (0)
; #define PG8_LDS_S(b) do { if constexpr (SLIVER) { Sf[0] = *(const PG8_LAS bf16x8*)(lds + STAGE_BYTES + (b) * 2048 + soff0); Sf[1] = *(const PG8_LAS bf16x8*)(lds + STAGE_BYTES + (b) * 2048 + (soff0 ^ 64)); } } while (0)
; #define PG8_WAIT_L(n) asm volatile("s_waitcnt lgkmcnt(" #n ")" ::: "memory")
; #define PG8_BAR __builtin_amdgcn_s_barrier()
; #define PG8_SCHED __builtin_amdgcn_sched_barrier(0)
; template <class Epi, class Sched, bool ALIGN_EPI = false, bool SP2 = false, bool SLIVER = false>
; __device__ __forceinline__ void gemm_phase(PG8_LAS unsigned char* lds, const Gemm g, const Sched& S, const Epi& E) {
;     ...
;         for (int t = 0; t < nt; t += 2) {
;             const bool last = (t == nt - 2);
;             const char* a1 = cA + (size_t)(t + 1) * kstep;
;             const char* a2 = last ? nA : cA + (size_t)(t + 2) * kstep; const char* b2 = last ? nB : cB + (size_t)(t + 2) * kstep;
;             const char* a3 = a2 + kstep; const char* b3 = b2 + kstep;
;     ...
;             PG8_LDA(At, 1, 1); PG8_LDS_S(1); PG8_STAGE(PG8_SB(1, 0), b3, voffB); PG8_STAGE(PG8_SB(1, 1), b3 + hstep, voffB); PG8_STAGE(PG8_SA(1, 0), a3, voffA);
;             PG8_WAIT_V89(); PG8_WAIT_L(0); PG8_BAR; PG8_MMA(1, 0, At, B0); PG8_MMA(1, 1, At, B1); PG8_MMA_S(); PG8_BAR; PG8_SCHED;
	s_setprio 0
	s_add_i32 s62, s62, s53
	s_mov_b32 m0, s62
	ds_read_b128 v[174:177], v149 offset:49152
	ds_read_b128 v[180:183], v149 offset:50176
	ds_read_b128 v[184:187], v149 offset:51200
	ds_read_b128 v[188:191], v149 offset:52224
	ds_read_b128 v[192:195], v149 offset:53248
	ds_read_b128 v[196:199], v149 offset:54272
	ds_read_b128 v[200:203], v149 offset:55296
	ds_read_b128 v[210:213], v149 offset:56320
	s_add_u32 s58, s78, 0x80
	s_addc_u32 s59, s79, 0
	global_load_lds_dwordx4 v132, s[58:59]
	s_add_i32 m0, s62, 0x2000
	s_add_i32 s62, s63, s53
	s_add_u32 s60, s78, 0x40080
	s_addc_u32 s61, s79, 0
	global_load_lds_dwordx4 v132, s[60:61]
	s_mov_b32 m0, s62
	s_add_u32 s36, s78, 0x80080
	s_addc_u32 s37, s79, 0
	global_load_lds_dwordx4 v132, s[36:37]
	s_add_i32 m0, s62, 0x2000
	s_nop 0
	s_add_u32 s58, s78, 0xc0080
	s_addc_u32 s59, s79, 0
	global_load_lds_dwordx4 v132, s[58:59]
	s_mov_b32 m0, s10
	s_nop 0
	s_add_u32 s60, s46, 0x80
	s_addc_u32 s61, s47, 0
	global_load_lds_dwordx4 v130, s[60:61]
	s_mov_b32 m0, s55
	s_nop 0
	s_add_u32 s36, s46, 0x40080
	s_addc_u32 s37, s47, 0
	global_load_lds_dwordx4 v130, s[36:37]
	s_waitcnt vmcnt(8)
	s_waitcnt lgkmcnt(0)
	s_setprio 1
	s_barrier
	v_mfma_f32_16x16x32_bf16 v[62:65], v[136:139], v[174:177], v[62:65]
	v_mfma_f32_16x16x32_bf16 v[62:65], v[140:143], v[180:183], v[62:65]
	v_mfma_f32_16x16x32_bf16 v[58:61], v[154:157], v[180:183], v[58:61]
	v_mfma_f32_16x16x32_bf16 v[58:61], v[150:153], v[174:177], v[58:61]
	v_mfma_f32_16x16x32_bf16 v[42:45], v[150:153], v[184:187], v[42:45]
	v_mfma_f32_16x16x32_bf16 v[42:45], v[154:157], v[188:191], v[42:45]
	v_mfma_f32_16x16x32_bf16 v[50:53], v[140:143], v[188:191], v[50:53]
	v_mfma_f32_16x16x32_bf16 v[50:53], v[136:139], v[184:187], v[50:53]
	v_mfma_f32_16x16x32_bf16 v[34:37], v[136:139], v[192:195], v[34:37]
	v_mfma_f32_16x16x32_bf16 v[34:37], v[140:143], v[196:199], v[34:37]
	v_mfma_f32_16x16x32_bf16 v[26:29], v[154:157], v[196:199], v[26:29]
	v_mfma_f32_16x16x32_bf16 v[26:29], v[150:153], v[192:195], v[26:29]
	v_mfma_f32_16x16x32_bf16 v[10:13], v[150:153], v[200:203], v[10:13]
	v_mfma_f32_16x16x32_bf16 v[10:13], v[154:157], v[210:213], v[10:13]
	v_mfma_f32_16x16x32_bf16 v[18:21], v[140:143], v[210:213], v[18:21]
	v_mfma_f32_16x16x32_bf16 v[18:21], v[136:139], v[200:203], v[18:21]
	s_setprio 0
	s_setprio 1
	v_mfma_f32_16x16x32_bf16 v[54:57], v[158:161], v[174:177], v[54:57]
	v_mfma_f32_16x16x32_bf16 v[54:57], v[162:165], v[180:183], v[54:57]
	v_mfma_f32_16x16x32_bf16 v[46:49], v[170:173], v[180:183], v[46:49]
	v_mfma_f32_16x16x32_bf16 v[46:49], v[166:169], v[174:177], v[46:49]
	v_mfma_f32_16x16x32_bf16 v[30:33], v[166:169], v[184:187], v[30:33]
	v_mfma_f32_16x16x32_bf16 v[30:33], v[170:173], v[188:191], v[30:33]
	v_mfma_f32_16x16x32_bf16 v[38:41], v[162:165], v[188:191], v[38:41]
	v_mfma_f32_16x16x32_bf16 v[38:41], v[158:161], v[184:187], v[38:41]
	v_mfma_f32_16x16x32_bf16 v[22:25], v[158:161], v[192:195], v[22:25]
	v_mfma_f32_16x16x32_bf16 v[22:25], v[162:165], v[196:199], v[22:25]
	v_mfma_f32_16x16x32_bf16 v[14:17], v[170:173], v[196:199], v[14:17]
	v_mfma_f32_16x16x32_bf16 v[14:17], v[166:169], v[192:195], v[14:17]
	v_mfma_f32_16x16x32_bf16 v[2:5], v[166:169], v[200:203], v[2:5]
	v_mfma_f32_16x16x32_bf16 v[2:5], v[170:173], v[210:213], v[2:5]
	v_mfma_f32_16x16x32_bf16 v[6:9], v[162:165], v[210:213], v[6:9]
	v_mfma_f32_16x16x32_bf16 v[6:9], v[158:161], v[200:203], v[6:9]
	s_barrier
	s_setprio 0
	s_add_i32 s76, s76, 2
	s_add_u32 s40, s40, 0x100
	s_addc_u32 s41, s41, 0
	s_add_u32 s68, s68, 0x100
	s_addc_u32 s69, s69, 0
	s_cmp_gt_u32 s76, 29
	s_cbranch_scc0 .LBB0_153
	s_and_b64 vcc, exec, s[48:49]
	s_cbranch_vccz .LBB0_156
	s_barrier

; #define PG8_SB(B) __builtin_amdgcn_rcpf(1.f + expneg(B))
; #define PG8_SB(B) __builtin_amdgcn_rcpf(1.f + expneg(B))
; #define PG8_STAGE(bufoff, gbase, voff) do { _Pragma("unroll") for (int _i = 0; _i < 2; ++_i) \
;         __builtin_amdgcn_global_load_lds((const unsigned*)((const char*)(gbase) + (size_t)_i * qstep + (voff)[0]), (PG8_LAS unsigned*)(lds + (bufoff) + ldsw + _i * 8192), 16, 0, 0); } while (0)
; #define PG8_LDA(dst, b, h) do { _Pragma("unroll") for (int m = 0; m < 4; ++m) _Pragma("unroll") for (int k = 0; k < 2; ++k) dst[m][k] = *(const PG8_LAS bf16x8*)(lds + PG8_SA(b, h) + aoff + m * 2048 + k * 1024); } while (0)
; #define PG8_MMA(ai, bj, At, Bt) do { __builtin_amdgcn_s_setprio(1); _Pragma("unroll") for (int m = 0; m < 4; ++m) _Pragma("unroll") for (int n = 0; n < 2; ++n) _Pragma("unroll") for (int k = 0; k < 2; ++k) \
;         acc[ai][bj][m][n] = __builtin_amdgcn_mfma_f32_16x16x32_bf16(Bt[n][k], At[m][k], acc[ai][bj][m][n], 0, 0, 0); __builtin_amdgcn_s_setprio(0); } while (0)
; #define PG8_WAIT_V89() do { if constexpr (SLIVER) PG8_WAIT_V(9); else PG8_WAIT_V(8); } while (0)
; #define PG8_LDS_S(b) do { if constexpr (SLIVER) { Sf[0] = *(const PG8_LAS bf16x8*)(lds + STAGE_BYTES + (b) * 2048 + soff0); Sf[1] = *(const PG8_LAS bf16x8*)(lds + STAGE_BYTES + (b) * 2048 + (soff0 ^ 64)); } } while (0)
; #define PG8_WAIT_L(n) asm volatile("s_waitcnt lgkmcnt(" #n ")" ::: "memory")
; #define PG8_BAR __builtin_amdgcn_s_barrier()
; #define PG8_SCHED __builtin_amdgcn_sched_barrier(0)
; template <class Epi, class Sched, bool ALIGN_EPI = false, bool SP2 = false, bool SLIVER = false>
; __device__ __forceinline__ void gemm_phase(PG8_LAS unsigned char* lds, const Gemm g, const Sched& S, const Epi& E) {
;     ...
;             PG8_WAIT_V89(); PG8_WAIT_L(0); PG8_BAR; PG8_MMA(0, 0, At, B0); PG8_MMA(0, 1, At, B1); PG8_BAR; PG8_SCHED;
;             PG8_LDA(At, 0, 1); PG8_LDS_S(0); PG8_STAGE(PG8_SB(0, 0), b2, voffB); PG8_STAGE(PG8_SB(0, 1), b2 + hstep, voffB); PG8_STAGE(PG8_SA(0, 0), a2, voffA);
;             PG8_WAIT_V89(); PG8_WAIT_L(0); PG8_BAR; PG8_MMA(1, 0, At, B0); PG8_MMA(1, 1, At, B1); PG8_MMA_S(); PG8_BAR; PG8_SCHED;
.Lgup_skipw0:
	s_waitcnt lgkmcnt(0)
	s_setprio 1
	s_barrier
	v_mfma_f32_16x16x32_bf16 v[126:129], v[130:133], v[172:175], v[126:129]
	v_mfma_f32_16x16x32_bf16 v[126:129], v[138:141], v[180:183], v[126:129]
	v_mfma_f32_16x16x32_bf16 v[118:121], v[152:155], v[180:183], v[118:121]
	v_mfma_f32_16x16x32_bf16 v[118:121], v[148:151], v[172:175], v[118:121]
	v_mfma_f32_16x16x32_bf16 v[102:105], v[148:151], v[184:187], v[102:105]
	v_mfma_f32_16x16x32_bf16 v[102:105], v[152:155], v[188:191], v[102:105]
	v_mfma_f32_16x16x32_bf16 v[110:113], v[138:141], v[188:191], v[110:113]
	v_mfma_f32_16x16x32_bf16 v[110:113], v[130:133], v[184:187], v[110:113]
	v_mfma_f32_16x16x32_bf16 v[94:97], v[130:133], v[192:195], v[94:97]
	v_mfma_f32_16x16x32_bf16 v[94:97], v[138:141], v[196:199], v[94:97]
	v_mfma_f32_16x16x32_bf16 v[86:89], v[152:155], v[196:199], v[86:89]
	v_mfma_f32_16x16x32_bf16 v[86:89], v[148:151], v[192:195], v[86:89]
	v_mfma_f32_16x16x32_bf16 v[70:73], v[148:151], v[200:203], v[70:73]
	v_mfma_f32_16x16x32_bf16 v[70:73], v[152:155], v[210:213], v[70:73]
	v_mfma_f32_16x16x32_bf16 v[78:81], v[138:141], v[210:213], v[78:81]
	v_mfma_f32_16x16x32_bf16 v[78:81], v[130:133], v[200:203], v[78:81]
	s_setprio 0
	s_setprio 1
	v_mfma_f32_16x16x32_bf16 v[122:125], v[156:159], v[172:175], v[122:125]
	v_mfma_f32_16x16x32_bf16 v[122:125], v[160:163], v[180:183], v[122:125]
	v_mfma_f32_16x16x32_bf16 v[114:117], v[168:171], v[180:183], v[114:117]
	v_mfma_f32_16x16x32_bf16 v[114:117], v[164:167], v[172:175], v[114:117]
	v_mfma_f32_16x16x32_bf16 v[98:101], v[164:167], v[184:187], v[98:101]
	v_mfma_f32_16x16x32_bf16 v[98:101], v[168:171], v[188:191], v[98:101]
	v_mfma_f32_16x16x32_bf16 v[106:109], v[160:163], v[188:191], v[106:109]
	v_mfma_f32_16x16x32_bf16 v[106:109], v[156:159], v[184:187], v[106:109]
	v_mfma_f32_16x16x32_bf16 v[90:93], v[156:159], v[192:195], v[90:93]
	v_mfma_f32_16x16x32_bf16 v[90:93], v[160:163], v[196:199], v[90:93]
	v_mfma_f32_16x16x32_bf16 v[82:85], v[168:171], v[196:199], v[82:85]
	v_mfma_f32_16x16x32_bf16 v[82:85], v[164:167], v[192:195], v[82:85]
	v_mfma_f32_16x16x32_bf16 v[66:69], v[164:167], v[200:203], v[66:69]
	v_mfma_f32_16x16x32_bf16 v[66:69], v[168:171], v[210:213], v[66:69]
	v_mfma_f32_16x16x32_bf16 v[74:77], v[160:163], v[210:213], v[74:77]
	v_mfma_f32_16x16x32_bf16 v[74:77], v[156:159], v[200:203], v[74:77]
	s_barrier
	s_setprio 0
	s_mov_b64 s[46:47], s[76:77]
	s_add_i32 s76, s78, s88
	s_mov_b32 m0, s76
	ds_read_b128 v[172:175], v147 offset:16384
	ds_read_b128 v[180:183], v147 offset:17408
	ds_read_b128 v[184:187], v147 offset:18432
	ds_read_b128 v[188:191], v147 offset:19456
	ds_read_b128 v[192:195], v147 offset:20480
	ds_read_b128 v[196:199], v147 offset:21504
	ds_read_b128 v[200:203], v147 offset:22528
	ds_read_b128 v[210:213], v147 offset:23552
	global_load_lds_dwordx4 v178, s[46:47]
	s_add_i32 m0, s76, 0x2000
	s_add_i32 s76, s79, s88
	s_add_u32 s58, s46, 0x40000
	s_addc_u32 s59, s47, 0
	global_load_lds_dwordx4 v178, s[58:59]
	s_mov_b32 m0, s76
	s_nop 0
	s_add_u32 s60, s46, 0x80000
	s_addc_u32 s61, s47, 0
	global_load_lds_dwordx4 v178, s[60:61]
	s_add_i32 m0, s76, 0x2000
	s_nop 0
	s_add_u32 s36, s46, 0xc0000
	s_addc_u32 s37, s47, 0
	global_load_lds_dwordx4 v178, s[36:37]
	s_mov_b32 m0, s45
	s_nop 0
	global_load_lds_dwordx4 v134, s[80:81]
	s_mov_b32 m0, s83
	s_nop 0
	s_add_u32 s58, s80, 0x40000
	s_addc_u32 s59, s81, 0
	global_load_lds_dwordx4 v134, s[58:59]
	s_cmp_eq_u32 s69, s101
	s_cbranch_scc1 .Lgup_skipw1
	s_waitcnt vmcnt(8)
.Lgup_skipw1:
	s_waitcnt lgkmcnt(0)
	s_setprio 1
	s_barrier
	v_mfma_f32_16x16x32_bf16 v[62:65], v[130:133], v[172:175], v[62:65]
	v_mfma_f32_16x16x32_bf16 v[62:65], v[138:141], v[180:183], v[62:65]
	v_mfma_f32_16x16x32_bf16 v[54:57], v[152:155], v[180:183], v[54:57]
	v_mfma_f32_16x16x32_bf16 v[54:57], v[148:151], v[172:175], v[54:57]
	v_mfma_f32_16x16x32_bf16 v[38:41], v[148:151], v[184:187], v[38:41]
	v_mfma_f32_16x16x32_bf16 v[38:41], v[152:155], v[188:191], v[38:41]
	v_mfma_f32_16x16x32_bf16 v[46:49], v[138:141], v[188:191], v[46:49]
	v_mfma_f32_16x16x32_bf16 v[46:49], v[130:133], v[184:187], v[46:49]
	v_mfma_f32_16x16x32_bf16 v[30:33], v[130:133], v[192:195], v[30:33]
	v_mfma_f32_16x16x32_bf16 v[30:33], v[138:141], v[196:199], v[30:33]
	v_mfma_f32_16x16x32_bf16 v[22:25], v[152:155], v[196:199], v[22:25]
	v_mfma_f32_16x16x32_bf16 v[22:25], v[148:151], v[192:195], v[22:25]
	v_mfma_f32_16x16x32_bf16 v[6:9], v[148:151], v[200:203], v[6:9]
	v_mfma_f32_16x16x32_bf16 v[6:9], v[152:155], v[210:213], v[6:9]
	v_mfma_f32_16x16x32_bf16 v[14:17], v[138:141], v[210:213], v[14:17]
	v_mfma_f32_16x16x32_bf16 v[14:17], v[130:133], v[200:203], v[14:17]
	s_setprio 0
	s_setprio 1
	v_mfma_f32_16x16x32_bf16 v[58:61], v[156:159], v[172:175], v[58:61]
	v_mfma_f32_16x16x32_bf16 v[58:61], v[160:163], v[180:183], v[58:61]
	v_mfma_f32_16x16x32_bf16 v[50:53], v[168:171], v[180:183], v[50:53]
	v_mfma_f32_16x16x32_bf16 v[50:53], v[164:167], v[172:175], v[50:53]
	v_mfma_f32_16x16x32_bf16 v[34:37], v[164:167], v[184:187], v[34:37]
	v_mfma_f32_16x16x32_bf16 v[34:37], v[168:171], v[188:191], v[34:37]
	v_mfma_f32_16x16x32_bf16 v[42:45], v[160:163], v[188:191], v[42:45]
	v_mfma_f32_16x16x32_bf16 v[42:45], v[156:159], v[184:187], v[42:45]
	v_mfma_f32_16x16x32_bf16 v[26:29], v[156:159], v[192:195], v[26:29]
	v_mfma_f32_16x16x32_bf16 v[26:29], v[160:163], v[196:199], v[26:29]
	v_mfma_f32_16x16x32_bf16 v[18:21], v[168:171], v[196:199], v[18:21]
	v_mfma_f32_16x16x32_bf16 v[18:21], v[164:167], v[192:195], v[18:21]
	v_mfma_f32_16x16x32_bf16 v[2:5], v[164:167], v[200:203], v[2:5]
	v_mfma_f32_16x16x32_bf16 v[2:5], v[168:171], v[210:213], v[2:5]
	v_mfma_f32_16x16x32_bf16 v[10:13], v[160:163], v[210:213], v[10:13]
	v_mfma_f32_16x16x32_bf16 v[10:13], v[156:159], v[200:203], v[10:13]
	s_barrier
; #define PG8_STAGE(bufoff, gbase, voff) do { _Pragma("unroll") for (int _i = 0; _i < 2; ++_i) \
;         __builtin_amdgcn_global_load_lds((const unsigned*)((const char*)(gbase) + (size_t)_i * qstep + (voff)[0]), (PG8_LAS unsigned*)(lds + (bufoff) + ldsw + _i * 8192), 16, 0, 0); } while (0)
; #define PG8_LDA(dst, b, h) do { _Pragma("unroll") for (int m = 0; m < 4; ++m) _Pragma("unroll") for (int k = 0; k < 2; ++k) dst[m][k] = *(const PG8_LAS bf16x8*)(lds + PG8_SA(b, h) + aoff + m * 2048 + k * 1024); } while (0)
; #define PG8_LDB(dst, b, h) do { _Pragma("unroll") for (int n = 0; n < 2; ++n) _Pragma("unroll") for (int k = 0; k < 2; ++k) dst[n][k] = *(const PG8_LAS bf16x8*)(lds + PG8_SB(b, h) + boff + n * 2048 + k * 1024); } while (0)
; #define PG8_MMA(ai, bj, At, Bt) do { __builtin_amdgcn_s_setprio(1); _Pragma("unroll") for (int m = 0; m < 4; ++m) _Pragma("unroll") for (int n = 0; n < 2; ++n) _Pragma("unroll") for (int k = 0; k < 2; ++k) \
;         acc[ai][bj][m][n] = __builtin_amdgcn_mfma_f32_16x16x32_bf16(Bt[n][k], At[m][k], acc[ai][bj][m][n], 0, 0, 0); __builtin_amdgcn_s_setprio(0); } while (0)
; #define PG8_WAIT_V89() do { if constexpr (SLIVER) PG8_WAIT_V(9); else PG8_WAIT_V(8); } while (0)
; #define PG8_STAGE_S(b, gbase) do { if constexpr (SLIVER) __builtin_amdgcn_global_load_lds((const unsigned*)((const char*)(gbase) + voffS), (PG8_LAS unsigned*)(lds + STAGE_BYTES + (b) * 2048 + wid * 256), 4, 0, 0); } while (0)
; #define PG8_WAIT_L(n) asm volatile("s_waitcnt lgkmcnt(" #n ")" ::: "memory")
; #define PG8_BAR __builtin_amdgcn_s_barrier()
; #define PG8_SCHED __builtin_amdgcn_sched_barrier(0)
; template <class Epi, class Sched, bool ALIGN_EPI = false, bool SP2 = false, bool SLIVER = false>
; __device__ __forceinline__ void gemm_phase(PG8_LAS unsigned char* lds, const Gemm g, const Sched& S, const Epi& E) {
;     ...
;             PG8_LDB(B0, 1, 0); PG8_LDB(B1, 1, 1); PG8_SCHED; PG8_LDA(At, 1, 0); PG8_STAGE(PG8_SA(0, 1), a2 + hstep, voffA); PG8_STAGE_S(0, s2);
;             PG8_WAIT_V89(); PG8_WAIT_L(0); PG8_BAR; PG8_MMA(0, 0, At, B0); PG8_MMA(0, 1, At, B1); PG8_BAR; PG8_SCHED;
	s_setprio 0
	s_add_i32 s76, 0, 0x18000
	v_add_u32_e32 v142, s76, v143
	s_add_i32 s77, 0, 0x1c000
	ds_read_b128 v[130:133], v142
	ds_read_b128 v[138:141], v142 offset:1024
	ds_read_b128 v[148:151], v142 offset:2048
	ds_read_b128 v[152:155], v142 offset:3072
	v_add_u32_e32 v142, s77, v143
	ds_read_b128 v[156:159], v142
	ds_read_b128 v[160:163], v142 offset:1024
	ds_read_b128 v[164:167], v142 offset:2048
	ds_read_b128 v[168:171], v142 offset:3072
	s_mov_b32 m0, s90
	ds_read_b128 v[172:175], v147 offset:32768
	ds_read_b128 v[180:183], v147 offset:33792
	ds_read_b128 v[184:187], v147 offset:34816
	ds_read_b128 v[188:191], v147 offset:35840
	ds_read_b128 v[192:195], v147 offset:36864
	ds_read_b128 v[196:199], v147 offset:37888
	ds_read_b128 v[200:203], v147 offset:38912
	ds_read_b128 v[210:213], v147 offset:39936
	s_add_u32 s60, s80, 0x80000
	s_addc_u32 s61, s81, 0
	global_load_lds_dwordx4 v134, s[60:61]
	s_mov_b32 m0, s91
	s_nop 0
	s_add_u32 s36, s80, 0xc0000
	s_addc_u32 s37, s81, 0
	global_load_lds_dwordx4 v134, s[36:37]
	s_waitcnt vmcnt(8)
	s_waitcnt lgkmcnt(0)
	s_setprio 1
	s_barrier
	v_mfma_f32_16x16x32_bf16 v[126:129], v[130:133], v[172:175], v[126:129]
	v_mfma_f32_16x16x32_bf16 v[126:129], v[138:141], v[180:183], v[126:129]
	v_mfma_f32_16x16x32_bf16 v[118:121], v[152:155], v[180:183], v[118:121]
	v_mfma_f32_16x16x32_bf16 v[118:121], v[148:151], v[172:175], v[118:121]
	v_mfma_f32_16x16x32_bf16 v[102:105], v[148:151], v[184:187], v[102:105]
	v_mfma_f32_16x16x32_bf16 v[102:105], v[152:155], v[188:191], v[102:105]
	v_mfma_f32_16x16x32_bf16 v[110:113], v[138:141], v[188:191], v[110:113]
	v_mfma_f32_16x16x32_bf16 v[110:113], v[130:133], v[184:187], v[110:113]
	v_mfma_f32_16x16x32_bf16 v[94:97], v[130:133], v[192:195], v[94:97]
	v_mfma_f32_16x16x32_bf16 v[94:97], v[138:141], v[196:199], v[94:97]
	v_mfma_f32_16x16x32_bf16 v[86:89], v[152:155], v[196:199], v[86:89]
	v_mfma_f32_16x16x32_bf16 v[86:89], v[148:151], v[192:195], v[86:89]
	v_mfma_f32_16x16x32_bf16 v[70:73], v[148:151], v[200:203], v[70:73]
	v_mfma_f32_16x16x32_bf16 v[70:73], v[152:155], v[210:213], v[70:73]
	v_mfma_f32_16x16x32_bf16 v[78:81], v[138:141], v[210:213], v[78:81]
	v_mfma_f32_16x16x32_bf16 v[78:81], v[130:133], v[200:203], v[78:81]
	s_setprio 0
	s_setprio 1
	v_mfma_f32_16x16x32_bf16 v[122:125], v[156:159], v[172:175], v[122:125]
	v_mfma_f32_16x16x32_bf16 v[122:125], v[160:163], v[180:183], v[122:125]
	v_mfma_f32_16x16x32_bf16 v[114:117], v[168:171], v[180:183], v[114:117]
	v_mfma_f32_16x16x32_bf16 v[114:117], v[164:167], v[172:175], v[114:117]
	v_mfma_f32_16x16x32_bf16 v[98:101], v[164:167], v[184:187], v[98:101]
	v_mfma_f32_16x16x32_bf16 v[98:101], v[168:171], v[188:191], v[98:101]
	v_mfma_f32_16x16x32_bf16 v[106:109], v[160:163], v[188:191], v[106:109]
	v_mfma_f32_16x16x32_bf16 v[106:109], v[156:159], v[184:187], v[106:109]
	v_mfma_f32_16x16x32_bf16 v[90:93], v[156:159], v[192:195], v[90:93]
	v_mfma_f32_16x16x32_bf16 v[90:93], v[160:163], v[196:199], v[90:93]
	v_mfma_f32_16x16x32_bf16 v[82:85], v[168:171], v[196:199], v[82:85]
	v_mfma_f32_16x16x32_bf16 v[82:85], v[164:167], v[192:195], v[82:85]
	v_mfma_f32_16x16x32_bf16 v[66:69], v[164:167], v[200:203], v[66:69]
	v_mfma_f32_16x16x32_bf16 v[66:69], v[168:171], v[210:213], v[66:69]
	v_mfma_f32_16x16x32_bf16 v[74:77], v[160:163], v[210:213], v[74:77]
	v_mfma_f32_16x16x32_bf16 v[74:77], v[156:159], v[200:203], v[74:77]
	s_barrier
; #define PG8_SB(B) __builtin_amdgcn_rcpf(1.f + expneg(B))
; #define PG8_SB(B) __builtin_amdgcn_rcpf(1.f + expneg(B))
; #define PG8_STAGE(bufoff, gbase, voff) do { _Pragma("unroll") for (int _i = 0; _i < 2; ++_i) \
;         __builtin_amdgcn_global_load_lds((const unsigned*)((const char*)(gbase) + (size_t)_i * qstep + (voff)[0]), (PG8_LAS unsigned*)(lds + (bufoff) + ldsw + _i * 8192), 16, 0, 0); } while (0)
; #define PG8_LDA(dst, b, h) do { _Pragma("unroll") for (int m = 0; m < 4; ++m) _Pragma("unroll") for (int k = 0; k < 2; ++k) dst[m][k] = *(const PG8_LAS bf16x8*)(lds + PG8_SA(b, h) + aoff + m * 2048 + k * 1024); } while (0)
; #define PG8_MMA(ai, bj, At, Bt) do { __builtin_amdgcn_s_setprio(1); _Pragma("unroll") for (int m = 0; m < 4; ++m) _Pragma("unroll") for (int n = 0; n < 2; ++n) _Pragma("unroll") for (int k = 0; k < 2; ++k) \
;         acc[ai][bj][m][n] = __builtin_amdgcn_mfma_f32_16x16x32_bf16(Bt[n][k], At[m][k], acc[ai][bj][m][n], 0, 0, 0); __builtin_amdgcn_s_setprio(0); } while (0)
; #define PG8_WAIT_V89() do { if constexpr (SLIVER) PG8_WAIT_V(9); else PG8_WAIT_V(8); } while (0)
; #define PG8_LDS_S(b) do { if constexpr (SLIVER) { Sf[0] = *(const PG8_LAS bf16x8*)(lds + STAGE_BYTES + (b) * 2048 + soff0); Sf[1] = *(const PG8_LAS bf16x8*)(lds + STAGE_BYTES + (b) * 2048 + (soff0 ^ 64)); } } while (0)
; #define PG8_WAIT_L(n) asm volatile("s_waitcnt lgkmcnt(" #n ")" ::: "memory")
; #define PG8_BAR __builtin_amdgcn_s_barrier()
; #define PG8_SCHED __builtin_amdgcn_sched_barrier(0)
; template <class Epi, class Sched, bool ALIGN_EPI = false, bool SP2 = false, bool SLIVER = false>
; __device__ __forceinline__ void gemm_phase(PG8_LAS unsigned char* lds, const Gemm g, const Sched& S, const Epi& E) {
;     ...
;         for (int t = 0; t < nt; t += 2) {
;             const bool last = (t == nt - 2);
;             const char* a1 = cA + (size_t)(t + 1) * kstep;
;             const char* a2 = last ? nA : cA + (size_t)(t + 2) * kstep; const char* b2 = last ? nB : cB + (size_t)(t + 2) * kstep;
;             const char* a3 = a2 + kstep; const char* b3 = b2 + kstep;
;     ...
;             PG8_LDA(At, 1, 1); PG8_LDS_S(1); PG8_STAGE(PG8_SB(1, 0), b3, voffB); PG8_STAGE(PG8_SB(1, 1), b3 + hstep, voffB); PG8_STAGE(PG8_SA(1, 0), a3, voffA);
;             PG8_WAIT_V89(); PG8_WAIT_L(0); PG8_BAR; PG8_MMA(1, 0, At, B0); PG8_MMA(1, 1, At, B1); PG8_MMA_S(); PG8_BAR; PG8_SCHED;
	s_setprio 0
	s_add_i32 s76, s76, s88
	s_mov_b32 m0, s76
	ds_read_b128 v[172:175], v147 offset:49152
	ds_read_b128 v[180:183], v147 offset:50176
	ds_read_b128 v[184:187], v147 offset:51200
	ds_read_b128 v[188:191], v147 offset:52224
	ds_read_b128 v[192:195], v147 offset:53248
	ds_read_b128 v[196:199], v147 offset:54272
	ds_read_b128 v[200:203], v147 offset:55296
	ds_read_b128 v[210:213], v147 offset:56320
	s_add_u32 s58, s46, 0x80
	s_addc_u32 s59, s47, 0
	global_load_lds_dwordx4 v178, s[58:59]
	s_add_i32 m0, s76, 0x2000
	s_add_i32 s76, s77, s88
	s_add_u32 s60, s46, 0x40080
	s_addc_u32 s61, s47, 0
	global_load_lds_dwordx4 v178, s[60:61]
	s_mov_b32 m0, s76
	s_add_u32 s36, s46, 0x80080
	s_addc_u32 s37, s47, 0
	global_load_lds_dwordx4 v178, s[36:37]
	s_add_i32 m0, s76, 0x2000
	s_nop 0
	s_add_u32 s58, s46, 0xc0080
	s_addc_u32 s59, s47, 0
	global_load_lds_dwordx4 v178, s[58:59]
	s_mov_b32 m0, s93
	s_nop 0
	s_add_u32 s60, s80, 0x80
	s_addc_u32 s61, s81, 0
	global_load_lds_dwordx4 v134, s[60:61]
	s_mov_b32 m0, s94
	s_nop 0
	s_add_u32 s36, s80, 0x40080
	s_addc_u32 s37, s81, 0
	global_load_lds_dwordx4 v134, s[36:37]
	s_waitcnt vmcnt(8)
	s_waitcnt lgkmcnt(0)
	s_setprio 1
	s_barrier
	v_mfma_f32_16x16x32_bf16 v[62:65], v[130:133], v[172:175], v[62:65]
	v_mfma_f32_16x16x32_bf16 v[62:65], v[138:141], v[180:183], v[62:65]
	v_mfma_f32_16x16x32_bf16 v[54:57], v[152:155], v[180:183], v[54:57]
	v_mfma_f32_16x16x32_bf16 v[54:57], v[148:151], v[172:175], v[54:57]
	v_mfma_f32_16x16x32_bf16 v[38:41], v[148:151], v[184:187], v[38:41]
	v_mfma_f32_16x16x32_bf16 v[38:41], v[152:155], v[188:191], v[38:41]
	v_mfma_f32_16x16x32_bf16 v[46:49], v[138:141], v[188:191], v[46:49]
	v_mfma_f32_16x16x32_bf16 v[46:49], v[130:133], v[184:187], v[46:49]
	v_mfma_f32_16x16x32_bf16 v[30:33], v[130:133], v[192:195], v[30:33]
	v_mfma_f32_16x16x32_bf16 v[30:33], v[138:141], v[196:199], v[30:33]
	v_mfma_f32_16x16x32_bf16 v[22:25], v[152:155], v[196:199], v[22:25]
	v_mfma_f32_16x16x32_bf16 v[22:25], v[148:151], v[192:195], v[22:25]
	v_mfma_f32_16x16x32_bf16 v[6:9], v[148:151], v[200:203], v[6:9]
	v_mfma_f32_16x16x32_bf16 v[6:9], v[152:155], v[210:213], v[6:9]
	v_mfma_f32_16x16x32_bf16 v[14:17], v[138:141], v[210:213], v[14:17]
	v_mfma_f32_16x16x32_bf16 v[14:17], v[130:133], v[200:203], v[14:17]
	s_setprio 0
	s_setprio 1
	v_mfma_f32_16x16x32_bf16 v[58:61], v[156:159], v[172:175], v[58:61]
	v_mfma_f32_16x16x32_bf16 v[58:61], v[160:163], v[180:183], v[58:61]
	v_mfma_f32_16x16x32_bf16 v[50:53], v[168:171], v[180:183], v[50:53]
	v_mfma_f32_16x16x32_bf16 v[50:53], v[164:167], v[172:175], v[50:53]
	v_mfma_f32_16x16x32_bf16 v[34:37], v[164:167], v[184:187], v[34:37]
	v_mfma_f32_16x16x32_bf16 v[34:37], v[168:171], v[188:191], v[34:37]
	v_mfma_f32_16x16x32_bf16 v[42:45], v[160:163], v[188:191], v[42:45]
	v_mfma_f32_16x16x32_bf16 v[42:45], v[156:159], v[184:187], v[42:45]
	v_mfma_f32_16x16x32_bf16 v[26:29], v[156:159], v[192:195], v[26:29]
	v_mfma_f32_16x16x32_bf16 v[26:29], v[160:163], v[196:199], v[26:29]
	v_mfma_f32_16x16x32_bf16 v[18:21], v[168:171], v[196:199], v[18:21]
	v_mfma_f32_16x16x32_bf16 v[18:21], v[164:167], v[192:195], v[18:21]
	v_mfma_f32_16x16x32_bf16 v[2:5], v[164:167], v[200:203], v[2:5]
	v_mfma_f32_16x16x32_bf16 v[2:5], v[168:171], v[210:213], v[2:5]
	v_mfma_f32_16x16x32_bf16 v[10:13], v[160:163], v[210:213], v[10:13]
	v_mfma_f32_16x16x32_bf16 v[10:13], v[156:159], v[200:203], v[10:13]
	s_barrier
	s_setprio 0
	s_add_i32 s69, s69, 2
	s_add_u32 s62, s62, 0x100
	s_addc_u32 s63, s63, 0
	s_add_u32 s67, s67, 0x100
	s_addc_u32 s68, s68, 0
	s_cmp_gt_u32 s69, 29
	s_cbranch_scc0 .LBB0_705
	s_and_b64 vcc, exec, s[42:43]
	s_cbranch_vccz .LBB0_708
	s_barrier
